# pre-pass HGRN units: 2 channels per thread, 4 token partitions, dwordx2 loads and dword stores
# speedup vs baseline: 1.0133x; 1.0014x over previous
.Lpre_init:
	v_and_b32_e32 v140, 63, v156
	v_lshlrev_b32_e32 v140, 3, v140
	v_lshlrev_b32_e32 v141, 3, v156
	v_and_b32_e32 v142, 63, v156
	v_lshlrev_b32_e32 v143, 1, v142
	v_lshlrev_b32_e32 v142, 2, v142
	v_lshlrev_b32_e32 v144, 2, v156
	v_lshrrev_b32_e32 v32, 6, v156
	s_nop 1
	v_readfirstlane_b32 s17, v32
	v_and_b32_e32 v146, 63, v156
	v_lshlrev_b32_e32 v146, 4, v146
	s_lshl_b32 s4, s17, 10
	s_add_u32 s4, s4, 0x800
	v_mov_b32_e32 v139, s4
	v_add_u32_e32 v147, s4, v146
	s_mov_b32 s10, 0x3fb8aa3b
	s_mov_b32 s11, 0xbfb8aa3b
	s_mov_b32 s12, 0x3f317218
	s_mov_b32 s13, 0x3d800000
	s_bfe_u32 s18, s88, 0x20001
	v_readlane_b32 s36, v253, 28
	v_readlane_b32 s37, v253, 29
	v_readlane_b32 s34, v253, 30
	v_readlane_b32 s35, v253, 31
	s_nop 3
	s_lshl_b32 s4, s18, 8
	s_add_u32 s36, s36, s4
	s_addc_u32 s37, s37, 0
	s_add_u32 s34, s34, s4
	s_addc_u32 s35, s35, 0
	s_nop 3
	global_load_dword v138, v142, s[34:35]
	global_load_dword v210, v142, s[36:37]
	global_load_dword v211, v142, s[36:37] offset:1024
	global_load_dword v212, v142, s[36:37] offset:2048
	global_load_dword v213, v142, s[36:37] offset:3072
	s_add_u32 s36, s36, 0x1000
	s_addc_u32 s37, s37, 0
	global_load_dword v214, v142, s[36:37]
	global_load_dword v215, v142, s[36:37] offset:1024
	global_load_dword v216, v142, s[36:37] offset:2048
	global_load_dword v217, v142, s[36:37] offset:3072
	s_add_u32 s36, s36, 0x1000
	s_addc_u32 s37, s37, 0
	global_load_dword v218, v142, s[36:37]
	global_load_dword v219, v142, s[36:37] offset:1024
	global_load_dword v220, v142, s[36:37] offset:2048
	global_load_dword v221, v142, s[36:37] offset:3072
	s_add_u32 s36, s36, 0x1000
	s_addc_u32 s37, s37, 0
	global_load_dword v128, v142, s[36:37]
	global_load_dword v129, v142, s[36:37] offset:1024
	global_load_dword v130, v142, s[36:37] offset:2048
	global_load_dword v131, v142, s[36:37] offset:3072
.Lpre_loop:
	s_lshr_b32 s4, s16, 9
	s_xor_b32 s4, s4, s88
	s_bitcmp1_b32 s4, 0
	s_cbranch_scc1 .Lpre_g_unit
	s_lshr_b32 s19, s16, 3
	s_lshl_b32 s4, s17, 4
	s_mov_b32 s23, 1
	s_cmp_lt_u32 s19, 0x400
	s_cbranch_scc1 .Lpre_h_full
	s_sub_u32 s20, s19, 0x400
	s_lshl_b32 s20, s20, 5
	s_add_u32 s20, s20, 0x10000
	s_add_u32 s20, s20, s4
	s_cmp_lt_u32 s4, 32
	s_cbranch_scc1 .Lpre_h_go
	s_mov_b32 s23, 0
	v_mov_b32_e32 v145, 0
	v_mov_b32_e32 v137, 0
	s_branch .Lpre_h_exch

.Lpre_h_go:
	s_lshl_b32 s21, s20, 11
	s_lshl_b32 s4, s18, 9
	s_add_u32 s21, s21, s4
	s_add_u32 s22, s21, 0xc180000
	s_add_u32 s24, s94, s22
	s_addc_u32 s25, s95, 0
	s_lshl_b32 s21, s20, 10
	s_lshl_b32 s4, s18, 8
	s_add_u32 s21, s21, s4
	s_add_u32 s22, s21, 0x8100000
	s_add_u32 s26, s94, s22
	s_addc_u32 s27, s95, 0
	s_mov_b64 s[28:29], s[26:27]
	s_add_u32 s22, s21, 0x2a540000
	s_add_u32 s30, s94, s22
	s_addc_u32 s31, s95, 0
	global_load_dwordx2 v[64:65], v140, s[24:25]
	global_load_dwordx2 v[66:67], v140, s[24:25] offset:2048
	s_add_u32 s24, s24, 0x1000
	s_addc_u32 s25, s25, 0
	global_load_dwordx2 v[68:69], v140, s[24:25]
	global_load_dwordx2 v[70:71], v140, s[24:25] offset:2048
	s_add_u32 s24, s24, 0x1000
	s_addc_u32 s25, s25, 0
	global_load_dwordx2 v[72:73], v140, s[24:25]
	global_load_dwordx2 v[74:75], v140, s[24:25] offset:2048
	s_add_u32 s24, s24, 0x1000
	s_addc_u32 s25, s25, 0
	global_load_dwordx2 v[76:77], v140, s[24:25]
	global_load_dwordx2 v[78:79], v140, s[24:25] offset:2048
	s_add_u32 s24, s24, 0x1000
	s_addc_u32 s25, s25, 0
	global_load_dwordx2 v[80:81], v140, s[24:25]
	global_load_dwordx2 v[82:83], v140, s[24:25] offset:2048
	s_add_u32 s24, s24, 0x1000
	s_addc_u32 s25, s25, 0
	global_load_dwordx2 v[84:85], v140, s[24:25]
	global_load_dwordx2 v[86:87], v140, s[24:25] offset:2048
	s_add_u32 s24, s24, 0x1000
	s_addc_u32 s25, s25, 0
	global_load_dwordx2 v[88:89], v140, s[24:25]
	global_load_dwordx2 v[90:91], v140, s[24:25] offset:2048
	s_add_u32 s24, s24, 0x1000
	s_addc_u32 s25, s25, 0
	global_load_dwordx2 v[92:93], v140, s[24:25]
	global_load_dwordx2 v[94:95], v140, s[24:25] offset:2048
	global_load_dword v0, v142, s[26:27]
	global_load_dword v1, v142, s[26:27] offset:1024
	global_load_dword v2, v142, s[26:27] offset:2048
	global_load_dword v3, v142, s[26:27] offset:3072
	s_add_u32 s26, s26, 0x1000
	s_addc_u32 s27, s27, 0
	global_load_dword v4, v142, s[26:27]
	global_load_dword v5, v142, s[26:27] offset:1024
	global_load_dword v6, v142, s[26:27] offset:2048
	global_load_dword v7, v142, s[26:27] offset:3072
	s_add_u32 s26, s26, 0x1000
	s_addc_u32 s27, s27, 0
	global_load_dword v8, v142, s[26:27]
	global_load_dword v9, v142, s[26:27] offset:1024
	global_load_dword v10, v142, s[26:27] offset:2048
	global_load_dword v11, v142, s[26:27] offset:3072
	s_add_u32 s26, s26, 0x1000
	s_addc_u32 s27, s27, 0
	global_load_dword v12, v142, s[26:27]
	global_load_dword v13, v142, s[26:27] offset:1024
	global_load_dword v14, v142, s[26:27] offset:2048
	global_load_dword v15, v142, s[26:27] offset:3072
	v_mov_b32_e32 v145, 0
	v_mov_b32_e32 v137, 0
	s_waitcnt vmcnt(28)
	v_log_f32_e32 v96, v64
	v_log_f32_e32 v97, v65
	v_log_f32_e32 v98, v66
	v_log_f32_e32 v99, v67
	v_log_f32_e32 v100, v68
	v_log_f32_e32 v101, v69
	v_log_f32_e32 v102, v70
	v_log_f32_e32 v103, v71
	v_sub_f32_e32 v64, 1.0, v64
	v_sub_f32_e32 v65, 1.0, v65
	v_sub_f32_e32 v66, 1.0, v66
	v_sub_f32_e32 v67, 1.0, v67
	v_sub_f32_e32 v68, 1.0, v68
	v_sub_f32_e32 v69, 1.0, v69
	v_sub_f32_e32 v70, 1.0, v70
	v_sub_f32_e32 v71, 1.0, v71
	v_mul_f32_e32 v96, s12, v96
	v_mul_f32_e32 v97, s12, v97
	v_mul_f32_e32 v98, s12, v98
	v_mul_f32_e32 v99, s12, v99
	v_mul_f32_e32 v100, s12, v100
	v_mul_f32_e32 v101, s12, v101
	v_mul_f32_e32 v102, s12, v102
	v_mul_f32_e32 v103, s12, v103
	v_add_f32_e32 v145, v145, v96
	v_add_f32_e32 v137, v137, v97
	v_add_f32_e32 v145, v145, v98
	v_add_f32_e32 v137, v137, v99
	v_add_f32_e32 v145, v145, v100
	v_add_f32_e32 v137, v137, v101
	v_add_f32_e32 v145, v145, v102
	v_add_f32_e32 v137, v137, v103
	s_waitcnt vmcnt(24)
	v_log_f32_e32 v104, v72
	v_log_f32_e32 v105, v73
	v_log_f32_e32 v106, v74
	v_log_f32_e32 v107, v75
	v_log_f32_e32 v108, v76
	v_log_f32_e32 v109, v77
	v_log_f32_e32 v110, v78
	v_log_f32_e32 v111, v79
	v_sub_f32_e32 v72, 1.0, v72
	v_sub_f32_e32 v73, 1.0, v73
	v_sub_f32_e32 v74, 1.0, v74
	v_sub_f32_e32 v75, 1.0, v75
	v_sub_f32_e32 v76, 1.0, v76
	v_sub_f32_e32 v77, 1.0, v77
	v_sub_f32_e32 v78, 1.0, v78
	v_sub_f32_e32 v79, 1.0, v79
	v_mul_f32_e32 v104, s12, v104
	v_mul_f32_e32 v105, s12, v105
	v_mul_f32_e32 v106, s12, v106
	v_mul_f32_e32 v107, s12, v107
	v_mul_f32_e32 v108, s12, v108
	v_mul_f32_e32 v109, s12, v109
	v_mul_f32_e32 v110, s12, v110
	v_mul_f32_e32 v111, s12, v111
	v_add_f32_e32 v145, v145, v104
	v_add_f32_e32 v137, v137, v105
	v_add_f32_e32 v145, v145, v106
	v_add_f32_e32 v137, v137, v107
	v_add_f32_e32 v145, v145, v108
	v_add_f32_e32 v137, v137, v109
	v_add_f32_e32 v145, v145, v110
	v_add_f32_e32 v137, v137, v111
	s_waitcnt vmcnt(20)
	v_log_f32_e32 v112, v80
	v_log_f32_e32 v113, v81
	v_log_f32_e32 v114, v82
	v_log_f32_e32 v115, v83
	v_log_f32_e32 v116, v84
	v_log_f32_e32 v117, v85
	v_log_f32_e32 v118, v86
	v_log_f32_e32 v119, v87
	v_sub_f32_e32 v80, 1.0, v80
	v_sub_f32_e32 v81, 1.0, v81
	v_sub_f32_e32 v82, 1.0, v82
	v_sub_f32_e32 v83, 1.0, v83
	v_sub_f32_e32 v84, 1.0, v84
	v_sub_f32_e32 v85, 1.0, v85
	v_sub_f32_e32 v86, 1.0, v86
	v_sub_f32_e32 v87, 1.0, v87
	v_mul_f32_e32 v112, s12, v112
	v_mul_f32_e32 v113, s12, v113
	v_mul_f32_e32 v114, s12, v114
	v_mul_f32_e32 v115, s12, v115
	v_mul_f32_e32 v116, s12, v116
	v_mul_f32_e32 v117, s12, v117
	v_mul_f32_e32 v118, s12, v118
	v_mul_f32_e32 v119, s12, v119
	v_add_f32_e32 v145, v145, v112
	v_add_f32_e32 v137, v137, v113
	v_add_f32_e32 v145, v145, v114
	v_add_f32_e32 v137, v137, v115
	v_add_f32_e32 v145, v145, v116
	v_add_f32_e32 v137, v137, v117
	v_add_f32_e32 v145, v145, v118
	v_add_f32_e32 v137, v137, v119
	s_waitcnt vmcnt(16)
	v_log_f32_e32 v120, v88
	v_log_f32_e32 v121, v89
	v_log_f32_e32 v122, v90
	v_log_f32_e32 v123, v91
	v_log_f32_e32 v124, v92
	v_log_f32_e32 v125, v93
	v_log_f32_e32 v126, v94
	v_log_f32_e32 v127, v95
	v_sub_f32_e32 v88, 1.0, v88
	v_sub_f32_e32 v89, 1.0, v89
	v_sub_f32_e32 v90, 1.0, v90
	v_sub_f32_e32 v91, 1.0, v91
	v_sub_f32_e32 v92, 1.0, v92
	v_sub_f32_e32 v93, 1.0, v93
	v_sub_f32_e32 v94, 1.0, v94
	v_sub_f32_e32 v95, 1.0, v95
	v_mul_f32_e32 v120, s12, v120
	v_mul_f32_e32 v121, s12, v121
	v_mul_f32_e32 v122, s12, v122
	v_mul_f32_e32 v123, s12, v123
	v_mul_f32_e32 v124, s12, v124
	v_mul_f32_e32 v125, s12, v125
	v_mul_f32_e32 v126, s12, v126
	v_mul_f32_e32 v127, s12, v127
	v_add_f32_e32 v145, v145, v120
	v_add_f32_e32 v137, v137, v121
	v_add_f32_e32 v145, v145, v122
	v_add_f32_e32 v137, v137, v123
	v_add_f32_e32 v145, v145, v124
	v_add_f32_e32 v137, v137, v125
	v_add_f32_e32 v145, v145, v126
	v_add_f32_e32 v137, v137, v127
.Lpre_h_exch:
	s_barrier
	v_mov_b32_e32 v32, v145
	v_mov_b32_e32 v33, v137
	ds_write_b64 v141, v[32:33]
	s_waitcnt lgkmcnt(0)
	s_barrier
	ds_read_b64 v[34:35], v140
	ds_read_b64 v[36:37], v140 offset:512
	ds_read_b64 v[38:39], v140 offset:1024
	ds_read_b64 v[40:41], v140 offset:1536
	s_waitcnt lgkmcnt(0)
	v_add_f32_e32 v42, v34, v36
	v_add_f32_e32 v43, v35, v37
	v_add_f32_e32 v42, v42, v38
	v_add_f32_e32 v43, v43, v39
	v_add_f32_e32 v42, v42, v40
	v_add_f32_e32 v43, v43, v41
	v_mov_b32_e32 v145, 0
	v_mov_b32_e32 v137, 0
	s_cmp_eq_u32 s17, 0
	s_cbranch_scc0 .Lpre_h_tpn
	s_mul_i32 s21, s19, 0xc00
	s_lshl_b32 s4, s18, 9
	s_add_u32 s21, s21, s4
	s_add_u32 s22, s21, 0x28d00000
	s_add_u32 s34, s94, s22
	s_addc_u32 s35, s95, 0
	v_mul_f32_e32 v44, s10, v42
	v_mul_f32_e32 v45, s10, v43
	v_exp_f32_e32 v44, v44
	v_exp_f32_e32 v45, v45
	s_nop 0
	global_store_dwordx2 v140, v[44:45], s[34:35]
	s_branch .Lpre_h_p2
.Lpre_h_tpn:
	v_mov_b32_e32 v145, v34
	v_mov_b32_e32 v137, v35
	s_cmp_lt_u32 s17, 2
	s_cbranch_scc1 .Lpre_h_p2
	v_add_f32_e32 v145, v145, v36
	v_add_f32_e32 v137, v137, v37
	s_cmp_lt_u32 s17, 3
	s_cbranch_scc1 .Lpre_h_p2
	v_add_f32_e32 v145, v145, v38
	v_add_f32_e32 v137, v137, v39
.Lpre_h_p2:
	s_cmp_eq_u32 s23, 0
	s_cbranch_scc1 .Lpre_h_next
	s_waitcnt vmcnt(0)
	v_add_f32_e32 v32, v145, v96
	v_add_f32_e32 v33, v137, v97
	v_add_f32_e32 v34, v32, v98
	v_add_f32_e32 v35, v33, v99
	v_mov_b32_e32 v145, v34
	v_mov_b32_e32 v137, v35
	v_mul_f32_e32 v32, s10, v32
	v_mul_f32_e32 v33, s10, v33
	v_mul_f32_e32 v34, s10, v34
	v_mul_f32_e32 v35, s10, v35
	v_exp_f32_e32 v36, v32
	v_exp_f32_e32 v37, v33
	v_exp_f32_e32 v38, v34
	v_exp_f32_e32 v39, v35
	v_exp_f32_e64 v40, -v32
	v_exp_f32_e64 v41, -v33
	v_exp_f32_e64 v42, -v34
	v_exp_f32_e64 v43, -v35
	v_lshlrev_b32_e32 v44, 16, v0
	v_and_b32_e32 v45, 0xffff0000, v0
	v_lshlrev_b32_e32 v46, 16, v1
	v_and_b32_e32 v47, 0xffff0000, v1
	v_mul_f32_e32 v36, v44, v36
	v_mul_f32_e32 v37, v45, v37
	v_mul_f32_e32 v38, v46, v38
	v_mul_f32_e32 v39, v47, v39
	v_mul_f32_e32 v40, v64, v40
	v_mul_f32_e32 v41, v65, v41
	v_mul_f32_e32 v42, v66, v42
	v_mul_f32_e32 v43, v67, v43
	v_cvt_pk_bf16_f32 v44, v36, v37
	v_cvt_pk_bf16_f32 v45, v40, v41
	v_cvt_pk_bf16_f32 v46, v38, v39
	v_cvt_pk_bf16_f32 v47, v42, v43
	s_nop 0
	global_store_dword v142, v44, s[28:29]
	global_store_dword v142, v45, s[30:31]
	global_store_dword v142, v46, s[28:29] offset:1024
	global_store_dword v142, v47, s[30:31] offset:1024
	v_add_f32_e32 v32, v145, v100
	v_add_f32_e32 v33, v137, v101
	v_add_f32_e32 v34, v32, v102
	v_add_f32_e32 v35, v33, v103
	v_mov_b32_e32 v145, v34
	v_mov_b32_e32 v137, v35
	v_mul_f32_e32 v32, s10, v32
	v_mul_f32_e32 v33, s10, v33
	v_mul_f32_e32 v34, s10, v34
	v_mul_f32_e32 v35, s10, v35
	v_exp_f32_e32 v36, v32
	v_exp_f32_e32 v37, v33
	v_exp_f32_e32 v38, v34
	v_exp_f32_e32 v39, v35
	v_exp_f32_e64 v40, -v32
	v_exp_f32_e64 v41, -v33
	v_exp_f32_e64 v42, -v34
	v_exp_f32_e64 v43, -v35
	v_lshlrev_b32_e32 v44, 16, v2
	v_and_b32_e32 v45, 0xffff0000, v2
	v_lshlrev_b32_e32 v46, 16, v3
	v_and_b32_e32 v47, 0xffff0000, v3
	v_mul_f32_e32 v36, v44, v36
	v_mul_f32_e32 v37, v45, v37
	v_mul_f32_e32 v38, v46, v38
	v_mul_f32_e32 v39, v47, v39
	v_mul_f32_e32 v40, v68, v40
	v_mul_f32_e32 v41, v69, v41
	v_mul_f32_e32 v42, v70, v42
	v_mul_f32_e32 v43, v71, v43
	v_cvt_pk_bf16_f32 v44, v36, v37
	v_cvt_pk_bf16_f32 v45, v40, v41
	v_cvt_pk_bf16_f32 v46, v38, v39
	v_cvt_pk_bf16_f32 v47, v42, v43
	s_nop 0
	global_store_dword v142, v44, s[28:29] offset:2048
	global_store_dword v142, v45, s[30:31] offset:2048
	global_store_dword v142, v46, s[28:29] offset:3072
	global_store_dword v142, v47, s[30:31] offset:3072
	s_add_u32 s28, s28, 0x1000
	s_addc_u32 s29, s29, 0
	s_add_u32 s30, s30, 0x1000
	s_addc_u32 s31, s31, 0
	v_add_f32_e32 v32, v145, v104
	v_add_f32_e32 v33, v137, v105
	v_add_f32_e32 v34, v32, v106
	v_add_f32_e32 v35, v33, v107
	v_mov_b32_e32 v145, v34
	v_mov_b32_e32 v137, v35
	v_mul_f32_e32 v32, s10, v32
	v_mul_f32_e32 v33, s10, v33
	v_mul_f32_e32 v34, s10, v34
	v_mul_f32_e32 v35, s10, v35
	v_exp_f32_e32 v36, v32
	v_exp_f32_e32 v37, v33
	v_exp_f32_e32 v38, v34
	v_exp_f32_e32 v39, v35
	v_exp_f32_e64 v40, -v32
	v_exp_f32_e64 v41, -v33
	v_exp_f32_e64 v42, -v34
	v_exp_f32_e64 v43, -v35
	v_lshlrev_b32_e32 v44, 16, v4
	v_and_b32_e32 v45, 0xffff0000, v4
	v_lshlrev_b32_e32 v46, 16, v5
	v_and_b32_e32 v47, 0xffff0000, v5
	v_mul_f32_e32 v36, v44, v36
	v_mul_f32_e32 v37, v45, v37
	v_mul_f32_e32 v38, v46, v38
	v_mul_f32_e32 v39, v47, v39
	v_mul_f32_e32 v40, v72, v40
	v_mul_f32_e32 v41, v73, v41
	v_mul_f32_e32 v42, v74, v42
	v_mul_f32_e32 v43, v75, v43
	v_cvt_pk_bf16_f32 v44, v36, v37
	v_cvt_pk_bf16_f32 v45, v40, v41
	v_cvt_pk_bf16_f32 v46, v38, v39
	v_cvt_pk_bf16_f32 v47, v42, v43
	s_nop 0
	global_store_dword v142, v44, s[28:29]
	global_store_dword v142, v45, s[30:31]
	global_store_dword v142, v46, s[28:29] offset:1024
	global_store_dword v142, v47, s[30:31] offset:1024
	v_add_f32_e32 v32, v145, v108
	v_add_f32_e32 v33, v137, v109
	v_add_f32_e32 v34, v32, v110
	v_add_f32_e32 v35, v33, v111
	v_mov_b32_e32 v145, v34
	v_mov_b32_e32 v137, v35
	v_mul_f32_e32 v32, s10, v32
	v_mul_f32_e32 v33, s10, v33
	v_mul_f32_e32 v34, s10, v34
	v_mul_f32_e32 v35, s10, v35
	v_exp_f32_e32 v36, v32
	v_exp_f32_e32 v37, v33
	v_exp_f32_e32 v38, v34
	v_exp_f32_e32 v39, v35
	v_exp_f32_e64 v40, -v32
	v_exp_f32_e64 v41, -v33
	v_exp_f32_e64 v42, -v34
	v_exp_f32_e64 v43, -v35
	v_lshlrev_b32_e32 v44, 16, v6
	v_and_b32_e32 v45, 0xffff0000, v6
	v_lshlrev_b32_e32 v46, 16, v7
	v_and_b32_e32 v47, 0xffff0000, v7
	v_mul_f32_e32 v36, v44, v36
	v_mul_f32_e32 v37, v45, v37
	v_mul_f32_e32 v38, v46, v38
	v_mul_f32_e32 v39, v47, v39
	v_mul_f32_e32 v40, v76, v40
	v_mul_f32_e32 v41, v77, v41
	v_mul_f32_e32 v42, v78, v42
	v_mul_f32_e32 v43, v79, v43
	v_cvt_pk_bf16_f32 v44, v36, v37
	v_cvt_pk_bf16_f32 v45, v40, v41
	v_cvt_pk_bf16_f32 v46, v38, v39
	v_cvt_pk_bf16_f32 v47, v42, v43
	s_nop 0
	global_store_dword v142, v44, s[28:29] offset:2048
	global_store_dword v142, v45, s[30:31] offset:2048
	global_store_dword v142, v46, s[28:29] offset:3072
	global_store_dword v142, v47, s[30:31] offset:3072
	s_add_u32 s28, s28, 0x1000
	s_addc_u32 s29, s29, 0
	s_add_u32 s30, s30, 0x1000
	s_addc_u32 s31, s31, 0
	v_add_f32_e32 v32, v145, v112
	v_add_f32_e32 v33, v137, v113
	v_add_f32_e32 v34, v32, v114
	v_add_f32_e32 v35, v33, v115
	v_mov_b32_e32 v145, v34
	v_mov_b32_e32 v137, v35
	v_mul_f32_e32 v32, s10, v32
	v_mul_f32_e32 v33, s10, v33
	v_mul_f32_e32 v34, s10, v34
	v_mul_f32_e32 v35, s10, v35
	v_exp_f32_e32 v36, v32
	v_exp_f32_e32 v37, v33
	v_exp_f32_e32 v38, v34
	v_exp_f32_e32 v39, v35
	v_exp_f32_e64 v40, -v32
	v_exp_f32_e64 v41, -v33
	v_exp_f32_e64 v42, -v34
	v_exp_f32_e64 v43, -v35
	v_lshlrev_b32_e32 v44, 16, v8
	v_and_b32_e32 v45, 0xffff0000, v8
	v_lshlrev_b32_e32 v46, 16, v9
	v_and_b32_e32 v47, 0xffff0000, v9
	v_mul_f32_e32 v36, v44, v36
	v_mul_f32_e32 v37, v45, v37
	v_mul_f32_e32 v38, v46, v38
	v_mul_f32_e32 v39, v47, v39
	v_mul_f32_e32 v40, v80, v40
	v_mul_f32_e32 v41, v81, v41
	v_mul_f32_e32 v42, v82, v42
	v_mul_f32_e32 v43, v83, v43
	v_cvt_pk_bf16_f32 v44, v36, v37
	v_cvt_pk_bf16_f32 v45, v40, v41
	v_cvt_pk_bf16_f32 v46, v38, v39
	v_cvt_pk_bf16_f32 v47, v42, v43
	s_nop 0
	global_store_dword v142, v44, s[28:29]
	global_store_dword v142, v45, s[30:31]
	global_store_dword v142, v46, s[28:29] offset:1024
	global_store_dword v142, v47, s[30:31] offset:1024
	v_add_f32_e32 v32, v145, v116
	v_add_f32_e32 v33, v137, v117
	v_add_f32_e32 v34, v32, v118
	v_add_f32_e32 v35, v33, v119
	v_mov_b32_e32 v145, v34
	v_mov_b32_e32 v137, v35
	v_mul_f32_e32 v32, s10, v32
	v_mul_f32_e32 v33, s10, v33
	v_mul_f32_e32 v34, s10, v34
	v_mul_f32_e32 v35, s10, v35
	v_exp_f32_e32 v36, v32
	v_exp_f32_e32 v37, v33
	v_exp_f32_e32 v38, v34
	v_exp_f32_e32 v39, v35
	v_exp_f32_e64 v40, -v32
	v_exp_f32_e64 v41, -v33
	v_exp_f32_e64 v42, -v34
	v_exp_f32_e64 v43, -v35
	v_lshlrev_b32_e32 v44, 16, v10
	v_and_b32_e32 v45, 0xffff0000, v10
	v_lshlrev_b32_e32 v46, 16, v11
	v_and_b32_e32 v47, 0xffff0000, v11
	v_mul_f32_e32 v36, v44, v36
	v_mul_f32_e32 v37, v45, v37
	v_mul_f32_e32 v38, v46, v38
	v_mul_f32_e32 v39, v47, v39
	v_mul_f32_e32 v40, v84, v40
	v_mul_f32_e32 v41, v85, v41
	v_mul_f32_e32 v42, v86, v42
	v_mul_f32_e32 v43, v87, v43
	v_cvt_pk_bf16_f32 v44, v36, v37
	v_cvt_pk_bf16_f32 v45, v40, v41
	v_cvt_pk_bf16_f32 v46, v38, v39
	v_cvt_pk_bf16_f32 v47, v42, v43
	s_nop 0
	global_store_dword v142, v44, s[28:29] offset:2048
	global_store_dword v142, v45, s[30:31] offset:2048
	global_store_dword v142, v46, s[28:29] offset:3072
	global_store_dword v142, v47, s[30:31] offset:3072
	s_add_u32 s28, s28, 0x1000
	s_addc_u32 s29, s29, 0
	s_add_u32 s30, s30, 0x1000
	s_addc_u32 s31, s31, 0
	v_add_f32_e32 v32, v145, v120
	v_add_f32_e32 v33, v137, v121
	v_add_f32_e32 v34, v32, v122
	v_add_f32_e32 v35, v33, v123
	v_mov_b32_e32 v145, v34
	v_mov_b32_e32 v137, v35
	v_mul_f32_e32 v32, s10, v32
	v_mul_f32_e32 v33, s10, v33
	v_mul_f32_e32 v34, s10, v34
	v_mul_f32_e32 v35, s10, v35
	v_exp_f32_e32 v36, v32
	v_exp_f32_e32 v37, v33
	v_exp_f32_e32 v38, v34
	v_exp_f32_e32 v39, v35
	v_exp_f32_e64 v40, -v32
	v_exp_f32_e64 v41, -v33
	v_exp_f32_e64 v42, -v34
	v_exp_f32_e64 v43, -v35
	v_lshlrev_b32_e32 v44, 16, v12
	v_and_b32_e32 v45, 0xffff0000, v12
	v_lshlrev_b32_e32 v46, 16, v13
	v_and_b32_e32 v47, 0xffff0000, v13
	v_mul_f32_e32 v36, v44, v36
	v_mul_f32_e32 v37, v45, v37
	v_mul_f32_e32 v38, v46, v38
	v_mul_f32_e32 v39, v47, v39
	v_mul_f32_e32 v40, v88, v40
	v_mul_f32_e32 v41, v89, v41
	v_mul_f32_e32 v42, v90, v42
	v_mul_f32_e32 v43, v91, v43
	v_cvt_pk_bf16_f32 v44, v36, v37
	v_cvt_pk_bf16_f32 v45, v40, v41
	v_cvt_pk_bf16_f32 v46, v38, v39
	v_cvt_pk_bf16_f32 v47, v42, v43
	s_nop 0
	global_store_dword v142, v44, s[28:29]
	global_store_dword v142, v45, s[30:31]
	global_store_dword v142, v46, s[28:29] offset:1024
	global_store_dword v142, v47, s[30:31] offset:1024
	v_add_f32_e32 v32, v145, v124
	v_add_f32_e32 v33, v137, v125
	v_add_f32_e32 v34, v32, v126
	v_add_f32_e32 v35, v33, v127
	v_mov_b32_e32 v145, v34
	v_mov_b32_e32 v137, v35
	v_mul_f32_e32 v32, s10, v32
	v_mul_f32_e32 v33, s10, v33
	v_mul_f32_e32 v34, s10, v34
	v_mul_f32_e32 v35, s10, v35
	v_exp_f32_e32 v36, v32
	v_exp_f32_e32 v37, v33
	v_exp_f32_e32 v38, v34
	v_exp_f32_e32 v39, v35
	v_exp_f32_e64 v40, -v32
	v_exp_f32_e64 v41, -v33
	v_exp_f32_e64 v42, -v34
	v_exp_f32_e64 v43, -v35
	v_lshlrev_b32_e32 v44, 16, v14
	v_and_b32_e32 v45, 0xffff0000, v14
	v_lshlrev_b32_e32 v46, 16, v15
	v_and_b32_e32 v47, 0xffff0000, v15
	v_mul_f32_e32 v36, v44, v36
	v_mul_f32_e32 v37, v45, v37
	v_mul_f32_e32 v38, v46, v38
	v_mul_f32_e32 v39, v47, v39
	v_mul_f32_e32 v40, v92, v40
	v_mul_f32_e32 v41, v93, v41
	v_mul_f32_e32 v42, v94, v42
	v_mul_f32_e32 v43, v95, v43
	v_cvt_pk_bf16_f32 v44, v36, v37
	v_cvt_pk_bf16_f32 v45, v40, v41
	v_cvt_pk_bf16_f32 v46, v38, v39
	v_cvt_pk_bf16_f32 v47, v42, v43
	s_nop 0
	global_store_dword v142, v44, s[28:29] offset:2048
	global_store_dword v142, v45, s[30:31] offset:2048
	global_store_dword v142, v46, s[28:29] offset:3072
	global_store_dword v142, v47, s[30:31] offset:3072
